# v29 + the rank-0 workgroup publishes its group's progress word as soon as its own group has arrived, before waiting for the neighbour group (breaks the serial release chain across the four groups of a
# baseline (speedup 1.0000x reference)
.LBB0_237:
	s_or_b64 exec, exec, s[20:21]
	v_mov_b32_e32 v243, 0
	v_readlane_b32 s4, v252, 25
	v_readlane_b32 s5, v252, 26
	s_andn2_b64 vcc, exec, s[4:5]
	s_cbranch_vccnz .Lpp0_load
	v_readlane_b32 s98, v252, 31
	s_cmp_eq_u32 s98, 0
	s_cbranch_scc1 .Lr0_join
	v_mul_lo_u32 v6, v3, v2
	s_mov_b32 s11, 0
	v_readlane_b32 s98, v253, 39
	v_readlane_b32 s99, v253, 40
	s_nop 4
.Lr0_top:
	global_load_dword v7, v27, s[98:99] sc1
	s_waitcnt vmcnt(0)
	v_cmp_ge_u32_e32 vcc, v7, v6
	s_cbranch_vccnz .Lr0_pub
	s_sleep 1
	s_add_i32 s11, s11, 1
	s_cmp_lt_u32 s11, 0x2000
	s_cbranch_scc1 .Lr0_top
.Lr0_pub:
	v_readlane_b32 s4, v252, 33
	v_readlane_b32 s5, v252, 34
	v_mov_b32_e32 v7, 1
	s_nop 4
	global_atomic_add v27, v7, s[4:5]
	v_mov_b32_e32 v243, 1
.Lr0_join:
	v_readlane_b32 s98, v253, 39
	v_readlane_b32 s99, v253, 40
	s_nop 4
	global_load_dword v242, v27, s[98:99] sc1
	v_readlane_b32 s4, v252, 27
	v_readlane_b32 s5, v252, 28
	s_nop 4
	global_load_dword v4, v27, s[4:5] sc1
	s_waitcnt vmcnt(0)
	v_cmp_lt_u32_e32 vcc, s75, v4
	s_cbranch_vccnz .LBB0_251
	s_mov_b32 s11, 1
	s_branch .LBB0_241

.LBB0_263:
	s_or_b64 exec, exec, s[20:21]
	v_readfirstlane_b32 s98, v243
	s_cmp_lg_u32 s98, 0
	s_cbranch_scc1 .LBB0_267
	v_readlane_b32 s4, v252, 31
	v_readlane_b32 s5, v252, 32
	s_andn2_b64 vcc, exec, s[4:5]
	s_cbranch_vccnz .LBB0_267
	s_mov_b64 s[28:29], exec
	v_mbcnt_lo_u32_b32 v2, s28, 0
	v_mbcnt_hi_u32_b32 v2, s29, v2
	v_cmp_eq_u32_e32 vcc, 0, v2
	s_and_saveexec_b64 s[20:21], vcc
	s_cbranch_execz .LBB0_266
	s_bcnt1_i32_b64 s11, s[28:29]
	v_readlane_b32 s4, v252, 33
	v_mov_b32_e32 v2, s11
	v_readlane_b32 s5, v252, 34
	s_nop 4
	global_atomic_add v27, v2, s[4:5]
